# tile loops: static schedule (L=blockIdx+k*gridDim) replaces atomic work-queue pop + LDS broadcast + store drain; one barrier per tile
# speedup vs baseline: 1.1078x; 1.0617x over previous
.LBB0_5:
	s_or_b64 exec, exec, s[2:3]
	s_load_dwordx2 s[2:3], s[0:1], 0x150
	s_waitcnt lgkmcnt(0)
	v_writelane_b32 v248, s2, 19
	s_cmp_ge_i32 s2, s3
	s_nop 0
	v_writelane_b32 v248, s3, 20
	s_cbranch_scc1 .LBB0_542
	s_load_dwordx16 s[76:91], s[0:1], 0x0
	s_load_dwordx16 s[52:67], s[0:1], 0x40
	s_load_dwordx16 s[4:19], s[0:1], 0xc0
	s_load_dwordx16 s[36:51], s[0:1], 0x100
	s_load_dwordx4 s[24:27], s[0:1], 0x140
	v_mbcnt_lo_u32_b32 v159, -1, 0
	v_mbcnt_hi_u32_b32 v160, -1, v159
	v_and_b32_e32 v2, 64, v160
	s_waitcnt lgkmcnt(0)
	v_writelane_b32 v248, s36, 21
	s_mov_b32 s97, 0
	v_mov_b32_e32 v147, 0
	v_writelane_b32 v248, s37, 22
	v_writelane_b32 v248, s38, 23
	v_writelane_b32 v248, s39, 24
	v_writelane_b32 v248, s40, 25
	v_writelane_b32 v248, s41, 26
	v_writelane_b32 v248, s42, 27
	v_writelane_b32 v248, s43, 28
	v_writelane_b32 v248, s44, 29
	v_writelane_b32 v248, s45, 30
	v_writelane_b32 v248, s46, 31
	v_writelane_b32 v248, s47, 32
	v_writelane_b32 v248, s48, 33
	v_writelane_b32 v248, s49, 34
	v_writelane_b32 v248, s50, 35
	v_writelane_b32 v248, s51, 36
	v_writelane_b32 v248, s24, 37
	s_mov_b32 s96, 0x800000
	v_mov_b32_e32 v1, 1
	v_writelane_b32 v248, s25, 38
	v_writelane_b32 v248, s26, 39
	v_writelane_b32 v248, s27, 40
	s_movk_i32 s93, 0x880
	v_readlane_b32 s21, v248, 0
	s_lshl_b32 s2, s21, 2
	s_add_u32 s0, s0, 0x158
	v_writelane_b32 v248, s2, 41
	s_addc_u32 s1, s1, 0
	v_writelane_b32 v248, s0, 42
	s_mov_b32 s27, 0x20000
	s_brev_b32 s26, -2
	v_writelane_b32 v248, s1, 43
	s_mov_b32 s33, 0x11000
	v_readlane_b32 s36, v248, 1
	v_readlane_b32 s46, v248, 11
	v_readlane_b32 s47, v248, 12
	s_add_u32 s0, s46, 0x1000
	s_addc_u32 s1, s47, 0
	v_readlane_b32 s37, v248, 2
	v_readlane_b32 s38, v248, 3
	v_readlane_b32 s39, v248, 4
	v_readlane_b32 s40, v248, 5
	v_readlane_b32 s41, v248, 6
	v_readlane_b32 s42, v248, 7
	v_readlane_b32 s43, v248, 8
	v_readlane_b32 s44, v248, 9
	v_readlane_b32 s45, v248, 10
	v_readlane_b32 s48, v248, 13
	v_readlane_b32 s49, v248, 14
	v_readlane_b32 s50, v248, 15
	v_readlane_b32 s51, v248, 16
	v_writelane_b32 v248, s0, 44
	s_cmpk_lt_i32 s21, 0x180
	s_mov_b32 s29, 0x22000
	v_writelane_b32 v248, s1, 45
	s_cselect_b64 s[0:1], -1, 0
	v_writelane_b32 v248, s0, 46
	s_mov_b32 s94, 0xa1000
	s_mov_b32 s92, 0x142000
	v_writelane_b32 v248, s1, 47
	s_mul_hi_i32 s0, s21, 0x2aaaaaab
	s_lshr_b32 s1, s0, 31
	s_ashr_i32 s0, s0, 4
	s_add_i32 s0, s0, s1
	s_mul_i32 s1, s0, 0x60
	s_sub_i32 s1, s21, s1
	s_lshl_b32 s22, s1, 5
	s_ashr_i32 s1, s0, 31
	s_lshl_b64 s[2:3], s[0:1], 10
	v_writelane_b32 v248, s2, 48
	s_ashr_i32 s23, s22, 31
	s_mul_i32 s1, s0, 0xc00
	v_writelane_b32 v248, s3, 49
	s_lshl_b64 s[2:3], s[22:23], 2
	s_add_u32 s2, s54, s2
	v_writelane_b32 v248, s52, 50
	s_addc_u32 s3, s55, s3
	s_add_i32 s1, s1, s22
	v_writelane_b32 v248, s53, 51
	v_writelane_b32 v248, s54, 52
	v_writelane_b32 v248, s55, 53
	v_writelane_b32 v248, s56, 54
	v_writelane_b32 v247, s66, 0
	v_writelane_b32 v248, s57, 55
	v_writelane_b32 v247, s67, 1
	v_writelane_b32 v248, s58, 56
	v_writelane_b32 v247, s2, 2
	v_writelane_b32 v248, s59, 57
	v_writelane_b32 v248, s60, 58
	v_writelane_b32 v247, s3, 3
	s_mov_b32 s2, s22
	v_writelane_b32 v247, s2, 4
	v_writelane_b32 v248, s61, 59
	v_writelane_b32 v248, s62, 60
	v_writelane_b32 v247, s3, 5
	v_writelane_b32 v247, s1, 6
	s_mul_i32 s0, s0, 3
	v_writelane_b32 v248, s63, 61
	v_writelane_b32 v247, s0, 7
	s_lshl_b32 s0, s21, 8
	v_writelane_b32 v248, s64, 62
	v_writelane_b32 v247, s0, 8
	s_add_u32 s0, s10, 0x2840000
	v_writelane_b32 v248, s65, 63
	s_addc_u32 s1, s11, 0
	v_readlane_b32 s60, v248, 21
	v_writelane_b32 v247, s0, 9
	v_readlane_b32 s61, v248, 22
	v_readlane_b32 s62, v248, 23
	v_writelane_b32 v247, s1, 10
	s_add_u32 s0, s60, 0x440000
	s_addc_u32 s1, s61, 0
	v_writelane_b32 v247, s0, 11
	v_readlane_b32 s63, v248, 24
	v_readlane_b32 s64, v248, 25
	v_writelane_b32 v247, s1, 12
	s_add_u32 s0, s14, 0x550000
	s_addc_u32 s1, s15, 0
	v_writelane_b32 v247, s0, 13
	v_readlane_b32 s65, v248, 26
	v_readlane_b32 s66, v248, 27
	v_writelane_b32 v247, s1, 14
	s_add_u32 s0, s44, 0x200
	s_addc_u32 s1, s45, 0
	v_writelane_b32 v247, s0, 15
	v_readlane_b32 s67, v248, 28
	v_readlane_b32 s68, v248, 29
	v_writelane_b32 v247, s1, 16
	s_add_u32 s0, s44, 0x1000
	s_addc_u32 s1, s45, 0
	v_writelane_b32 v247, s0, 17
	v_readlane_b32 s69, v248, 30
	v_readlane_b32 s70, v248, 31
	v_writelane_b32 v247, s1, 18
	s_add_u32 s0, s44, 0x1100
	s_addc_u32 s1, s45, 0
	v_writelane_b32 v247, s0, 19
	v_readlane_b32 s71, v248, 32
	v_readlane_b32 s72, v248, 33
	v_writelane_b32 v247, s1, 20
	s_add_u32 s0, s44, 0x1200
	s_addc_u32 s1, s45, 0
	v_writelane_b32 v247, s0, 21
	v_readlane_b32 s73, v248, 34
	v_readlane_b32 s74, v248, 35
	v_writelane_b32 v247, s1, 22
	s_add_u32 s0, s44, 0x1300
	s_addc_u32 s1, s45, 0
	v_writelane_b32 v247, s0, 23
	s_cmp_eq_u32 s20, 15
	v_readlane_b32 s75, v248, 36
	v_writelane_b32 v247, s1, 24
	s_cselect_b64 s[0:1], -1, 0
	v_writelane_b32 v247, s0, 25
	s_cmp_eq_u32 s20, 14
	s_mov_b32 s28, 0x1e3000
	v_writelane_b32 v247, s1, 26
	s_cselect_b64 s[0:1], -1, 0
	v_writelane_b32 v247, s0, 27
	s_cmp_eq_u32 s20, 13
	s_movk_i32 s95, 0xfefe
	v_writelane_b32 v247, s1, 28
	s_cselect_b64 s[0:1], -1, 0
	v_writelane_b32 v247, s0, 29
	s_cmp_eq_u32 s20, 12
	v_mov_b32_e32 v148, 0x358637bd
	v_writelane_b32 v247, s1, 30
	s_cselect_b64 s[0:1], -1, 0
	v_writelane_b32 v247, s0, 31
	s_cmp_eq_u32 s20, 11
	v_mov_b32_e32 v149, 0x10a00
	v_writelane_b32 v247, s1, 32
	s_cselect_b64 s[0:1], -1, 0
	v_writelane_b32 v247, s0, 33
	s_cmp_eq_u32 s20, 10
	s_mov_b32 s31, 0x7f800000
	v_writelane_b32 v247, s1, 34
	s_cselect_b64 s[0:1], -1, 0
	v_writelane_b32 v247, s0, 35
	s_cmp_eq_u32 s20, 9
	v_mov_b32_e32 v154, 0xbf1f24be
	v_writelane_b32 v247, s1, 36
	s_cselect_b64 s[0:1], -1, 0
	v_writelane_b32 v247, s0, 37
	s_cmp_eq_u32 s20, 8
	v_mov_b32_e32 v155, 0x3e642e9d
	v_writelane_b32 v247, s1, 38
	s_cselect_b64 s[0:1], -1, 0
	v_writelane_b32 v247, s0, 39
	s_cmp_eq_u32 s20, 7
	s_mov_b32 s58, 0xbf1f24be
	v_writelane_b32 v247, s1, 40
	s_cselect_b64 s[0:1], -1, 0
	v_writelane_b32 v247, s0, 41
	s_cmp_eq_u32 s20, 6
	s_movk_i32 s30, 0x240
	v_writelane_b32 v247, s1, 42
	s_cselect_b64 s[0:1], -1, 0
	v_writelane_b32 v247, s0, 43
	s_cmp_eq_u32 s20, 5
	v_mov_b32_e32 v156, 0x3e91f4c4
	v_writelane_b32 v247, s1, 44
	s_cselect_b64 s[0:1], -1, 0
	v_writelane_b32 v247, s0, 45
	s_cmp_eq_u32 s20, 4
	v_mov_b32_e32 v157, 0x12010
	v_writelane_b32 v247, s1, 46
	s_cselect_b64 s[0:1], -1, 0
	v_writelane_b32 v247, s0, 47
	s_cmp_eq_u32 s20, 3
	v_mov_b32_e32 v158, 0x12014
	v_writelane_b32 v247, s1, 48
	s_cselect_b64 s[0:1], -1, 0
	v_writelane_b32 v247, s0, 49
	s_cmp_eq_u32 s20, 2
	v_add_u32_e32 v161, 64, v2
	v_writelane_b32 v247, s1, 50
	s_cselect_b64 s[0:1], -1, 0
	v_writelane_b32 v247, s0, 51
	s_cmp_eq_u32 s20, 1
	v_xor_b32_e32 v162, 32, v160
	v_writelane_b32 v247, s1, 52
	s_cselect_b64 s[0:1], -1, 0
	v_writelane_b32 v247, s0, 53
	s_cmp_eq_u32 s20, 0
	v_xor_b32_e32 v163, 16, v160
	v_writelane_b32 v247, s1, 54
	s_cselect_b64 s[0:1], -1, 0
	v_writelane_b32 v247, s0, 55
	v_xor_b32_e32 v164, 8, v160
	v_xor_b32_e32 v165, 4, v160
	v_writelane_b32 v247, s1, 56
	s_lshl_b32 s0, s20, 8
	s_add_u32 s0, s44, s0
	s_addc_u32 s1, s45, 0
	s_add_u32 s2, s0, 0x1400
	s_addc_u32 s3, s1, 0
	v_writelane_b32 v247, s2, 57
	s_add_u32 s0, s0, 0x2400
	s_addc_u32 s1, s1, 0
	v_writelane_b32 v247, s3, 58
	v_writelane_b32 v247, s0, 59
	s_mov_b32 s3, 0x33000
	v_xor_b32_e32 v166, 2, v160
	v_writelane_b32 v247, s1, 60
	s_add_u32 s0, s44, 0x3400
	s_addc_u32 s1, s45, 0
	v_writelane_b32 v247, s0, 61
	v_xor_b32_e32 v167, 1, v160
	v_mov_b32_e32 v150, 0x12000
	v_writelane_b32 v247, s1, 62
	s_add_u32 s0, s44, 0x3500
	s_addc_u32 s1, s45, 0
	v_writelane_b32 v247, s0, 63
	v_mov_b32_e32 v168, 0x80
	v_mov_b32_e32 v169, 0xf149f2ca
	v_writelane_b32 v246, s1, 0
	s_lshl_b32 s0, s21, 9
	v_writelane_b32 v246, s0, 1
	s_add_u32 s0, s6, 4
	s_addc_u32 s1, s7, 0
	v_writelane_b32 v246, s0, 2
	v_mov_b32_e32 v170, 0x10800
	v_mov_b32_e32 v171, 0x2000
	v_writelane_b32 v246, s1, 3
	v_writelane_b32 v246, s76, 4
	v_mov_b32_e32 v172, 0x7fc00000
	v_mov_b32_e32 v173, 0xffc00000
	v_writelane_b32 v246, s77, 5
	v_writelane_b32 v246, s78, 6
	v_writelane_b32 v246, s79, 7
	v_writelane_b32 v246, s80, 8
	v_writelane_b32 v246, s81, 9
	v_writelane_b32 v246, s82, 10
	v_writelane_b32 v246, s83, 11
	v_writelane_b32 v246, s84, 12
	v_writelane_b32 v246, s85, 13
	v_writelane_b32 v246, s86, 14
	v_writelane_b32 v246, s87, 15
	v_writelane_b32 v246, s88, 16
	v_writelane_b32 v246, s89, 17
	v_mov_b32_e32 v174, 0x461c4000
	v_mov_b32_e32 v175, 0x37000000
	v_mov_b32_e32 v176, 0x7f800000
	v_writelane_b32 v246, s90, 18
	v_writelane_b32 v246, s91, 19
	v_readlane_b32 s20, v248, 42
	v_readlane_b32 s21, v248, 43
	s_nop 1
	s_load_dword s20, s[20:21], 0x0
	s_waitcnt lgkmcnt(0)
	v_writelane_b32 v246, s20, 41
	s_branch .LBB0_10

.LBB0_10:
	v_readlane_b32 s20, v248, 0
	s_nop 1
	v_writelane_b32 v246, s20, 40
	v_readlane_b32 s0, v248, 19
	v_readlane_b32 s1, v248, 20
	s_movk_i32 s53, 0x140
	s_mov_b64 s[22:23], -1
	s_mov_b64 s[20:21], 0
	s_cmp_lt_i32 s0, 1
	s_mov_b64 s[0:1], 0
	s_cbranch_scc1 .LBB0_18
	v_readlane_b32 s0, v248, 19
	s_cmp_gt_i32 s0, 13
	v_readlane_b32 s1, v248, 20
	s_cbranch_scc0 .LBB0_21
	v_readlane_b32 s0, v248, 19
	v_readlane_b32 s1, v248, 20
	s_cmp_eq_u32 s0, 14
	s_mov_b64 s[0:1], -1
	s_cbranch_scc0 .LBB0_17
	s_waitcnt lgkmcnt(11)
	v_mov_b32_e32 v3, v0
	v_readlane_b32 s0, v248, 41
	v_ashrrev_i32_e32 v2, 6, v3
	s_movk_i32 s34, 0x2800
	v_add_u32_e32 v2, s0, v2
	v_cmp_gt_i32_e32 vcc, s34, v2
	s_and_saveexec_b64 s[22:23], vcc
	s_mov_b32 s52, 0x3a800000
	s_movk_i32 s35, 0x27ff
	s_cbranch_execz .LBB0_16
	v_readlane_b32 s0, v248, 42
	v_cmp_lt_i32_e32 vcc, v162, v161
	v_readlane_b32 s1, v248, 43
	s_load_dword s0, s[0:1], 0x0
	v_cndmask_b32_e32 v4, v160, v162, vcc
	v_cmp_lt_i32_e32 vcc, v163, v161
	v_lshlrev_b32_e32 v50, 2, v4
	v_lshlrev_b32_e32 v3, 4, v3
	v_cndmask_b32_e32 v4, v160, v163, vcc
	v_cmp_lt_i32_e32 vcc, v164, v161
	v_lshlrev_b32_e32 v51, 2, v4
	v_readlane_b32 s36, v248, 1
	v_cndmask_b32_e32 v4, v160, v164, vcc
	v_cmp_lt_i32_e32 vcc, v165, v161
	v_lshlrev_b32_e32 v52, 2, v4
	v_and_b32_e32 v146, 0x3f0, v3
	v_cndmask_b32_e32 v4, v160, v165, vcc
	v_cmp_lt_i32_e32 vcc, v166, v161
	v_lshlrev_b32_e32 v53, 2, v4
	v_readlane_b32 s40, v248, 5
	v_cndmask_b32_e32 v4, v160, v166, vcc
	v_cmp_lt_i32_e32 vcc, v167, v161
	v_lshlrev_b32_e32 v54, 2, v4
	v_readlane_b32 s41, v248, 6
	v_cndmask_b32_e32 v4, v160, v167, vcc
	v_readlane_b32 s42, v248, 7
	v_readlane_b32 s43, v248, 8
	s_waitcnt lgkmcnt(0)
	s_lshl_b32 s2, s0, 2
	v_lshlrev_b32_e32 v55, 2, v4
	v_lshl_add_u64 v[38:39], s[40:41], 0, v[146:147]
	v_lshl_add_u64 v[40:41], s[42:43], 0, v[146:147]
	s_mov_b64 s[24:25], 0
	v_readlane_b32 s37, v248, 2
	v_readlane_b32 s38, v248, 3
	v_readlane_b32 s39, v248, 4
	v_readlane_b32 s44, v248, 9
	v_readlane_b32 s45, v248, 10
	v_readlane_b32 s46, v248, 11
	v_readlane_b32 s47, v248, 12
	v_readlane_b32 s48, v248, 13
	v_readlane_b32 s49, v248, 14
	v_readlane_b32 s50, v248, 15
	v_readlane_b32 s51, v248, 16

.LBB0_25:
	v_readlane_b32 s34, v246, 40
	v_readlane_b32 s35, v246, 41
	s_waitcnt lgkmcnt(0)
	s_barrier
	s_add_i32 s35, s34, s35
	v_writelane_b32 v246, s35, 40
	s_and_b32 s35, s34, 7
	s_lshl_b32 s35, s35, 16
	s_lshr_b32 s22, s34, 3
	s_or_b32 s22, s22, s35
	s_cmp_lt_u32 s34, 128
	s_cselect_b32 s22, s22, -1
	s_mov_b32 s39, 0xf000
	s_cmp_lt_i32 s22, 0
	s_cbranch_scc1 .LBB0_24
	s_lshr_b32 s0, s22, 12
	s_and_b32 s0, s0, 0x7fff0
	s_and_b32 s1, s22, 0xffff
	s_add_i32 s23, s0, s1
	s_lshr_b32 s1, s23, 5
	s_bfe_u32 s0, s23, 0x20003
	s_and_b32 s1, s1, 1
	s_lshr_b32 s23, s23, 6
	s_cmp_eq_u32 s1, 0
	s_mul_i32 s35, s23, 0x220000
	s_cselect_b32 s24, s68, s70
	s_cselect_b32 s25, s69, s71
	s_mul_hi_u32 s34, s23, 0x220000
	s_add_u32 s35, s62, s35
	s_addc_u32 s34, s63, s34
	s_lshl_b32 s22, s22, 7
	s_and_b32 s22, s22, 0x380
	s_mul_i32 s38, s22, 0x880
	s_add_u32 s35, s35, s38
	s_addc_u32 s34, s34, 0
	s_lshl_b32 s38, s0, 9
	v_mov_b32_e32 v38, v0
	s_add_u32 s40, s35, s38
	s_addc_u32 s38, s34, 0
	v_ashrrev_i32_e32 v34, 3, v38
	v_lshlrev_b32_e32 v3, 3, v38
	v_mul_lo_u32 v2, v34, s53
	v_and_b32_e32 v35, 56, v3
	s_movk_i32 s34, 0x440
	v_or_b32_e32 v2, v2, v35
	v_mul_lo_u32 v3, v34, s34
	v_or_b32_e32 v3, v3, v35
	v_lshlrev_b32_e32 v185, 1, v2
	s_and_b32 s25, s25, 0xffff
	s_movk_i32 s34, 0x5000
	v_lshlrev_b32_e32 v183, 1, v3
	s_and_b32 s41, s38, 0xffff
	s_mov_b32 s42, s26
	s_mov_b32 s43, s27
	buffer_load_dwordx4 v[2:5], v185, s[24:27], 0 offen
	buffer_load_dwordx4 v[6:9], v183, s[40:43], 0 offen
	buffer_load_dwordx4 v[10:13], v185, s[24:27], s34 offen
	buffer_load_dwordx4 v[14:17], v183, s[40:43], s33 offen
	s_mov_b32 s34, 0xa000
	buffer_load_dwordx4 v[18:21], v185, s[24:27], s34 offen
	buffer_load_dwordx4 v[22:25], v183, s[40:43], s29 offen
	buffer_load_dwordx4 v[26:29], v185, s[24:27], s39 offen
	buffer_load_dwordx4 v[30:33], v183, s[40:43], s3 offen
	s_movk_i32 s35, 0x90
	v_mul_lo_u32 v34, v34, s35
	s_add_u32 s44, s40, 0x80
	v_lshl_add_u32 v180, v35, 1, v34
	s_addc_u32 s34, s38, 0
	s_and_b32 s45, s34, 0xffff
	s_movk_i32 s34, 0x80
	s_mov_b32 s46, s26
	s_mov_b32 s47, s27
	v_bfe_u32 v151, v38, 5, 1
	v_add_u32_e32 v184, 0xd800, v180
	s_waitcnt vmcnt(7)
	ds_write_b128 v180, v[2:5]
	s_waitcnt vmcnt(6)
	ds_write_b128 v180, v[6:9] offset:36864
	s_waitcnt vmcnt(5)
	ds_write_b128 v180, v[10:13] offset:4608
	s_waitcnt vmcnt(4)
	ds_write_b128 v180, v[14:17] offset:41472
	s_waitcnt vmcnt(3)
	ds_write_b128 v180, v[18:21] offset:9216
	s_waitcnt vmcnt(2)
	ds_write_b128 v180, v[22:25] offset:46080
	s_waitcnt vmcnt(1)
	ds_write_b128 v180, v[26:29] offset:13824
	s_waitcnt vmcnt(0)
	ds_write_b128 v180, v[30:33] offset:50688
	buffer_load_dwordx4 v[2:5], v185, s[24:27], s34 offen
	buffer_load_dwordx4 v[34:37], v183, s[44:47], 0 offen
	s_movk_i32 s34, 0x5080
	buffer_load_dwordx4 v[118:121], v185, s[24:27], s34 offen
	buffer_load_dwordx4 v[114:117], v183, s[44:47], s33 offen
	s_mov_b32 s34, 0xa080
	buffer_load_dwordx4 v[110:113], v185, s[24:27], s34 offen
	buffer_load_dwordx4 v[102:105], v183, s[44:47], s29 offen
	s_mov_b32 s34, 0xf080
	buffer_load_dwordx4 v[106:109], v185, s[24:27], s34 offen
	buffer_load_dwordx4 v[86:89], v183, s[44:47], s3 offen
	s_add_u32 s44, s40, 0x100
	s_addc_u32 s34, s38, 0
	s_and_b32 s45, s34, 0xffff
	s_movk_i32 s34, 0x100
	v_ashrrev_i32_e32 v6, 1, v38
	buffer_load_dwordx4 v[98:101], v185, s[24:27], s34 offen
	buffer_load_dwordx4 v[90:93], v183, s[44:47], 0 offen
	s_movk_i32 s34, 0x5100
	v_and_b32_e32 v181, 0xffffffc0, v6
	buffer_load_dwordx4 v[94:97], v185, s[24:27], s34 offen
	buffer_load_dwordx4 v[82:85], v183, s[44:47], s33 offen
	s_mov_b32 s34, 0xa100
	v_and_or_b32 v7, v38, 31, v181
	v_lshlrev_b32_e32 v6, 4, v151
	buffer_load_dwordx4 v[78:81], v185, s[24:27], s34 offen
	buffer_load_dwordx4 v[74:77], v183, s[44:47], s29 offen
	s_mov_b32 s34, 0xf100
	v_mad_u64_u32 v[152:153], s[42:43], v7, s35, v[6:7]
	s_add_u32 s40, s40, 0x180
	buffer_load_dwordx4 v[70:73], v185, s[24:27], s34 offen
	buffer_load_dwordx4 v[66:69], v183, s[44:47], s3 offen
	v_and_b32_e32 v153, 0x5f, v38
	s_addc_u32 s34, s38, 0
	v_mul_u32_u24_e32 v7, 0x48, v153
	s_and_b32 s41, s34, 0xffff
	s_movk_i32 s34, 0x180
	s_waitcnt lgkmcnt(0)
	s_barrier
	v_lshl_add_u32 v182, v7, 1, v6
	ds_read_b128 v[38:41], v152 offset:4608
	ds_read_b128 v[42:45], v182 offset:41472
	ds_read_b128 v[6:9], v152
	ds_read_b128 v[138:141], v152 offset:32
	ds_read_b128 v[126:129], v152 offset:4640
	ds_read_b128 v[10:13], v182 offset:36864
	ds_read_b128 v[134:137], v182 offset:36896
	ds_read_b128 v[130:133], v182 offset:41504
	buffer_load_dwordx4 v[122:125], v185, s[24:27], s34 offen
	s_mov_b32 s42, s26
	s_mov_b32 s43, s27
	s_waitcnt lgkmcnt(2)
	v_mfma_f32_32x32x16_bf16 v[18:33], v[6:9], v[10:13], 0
	s_waitcnt vmcnt(16)
	ds_write_b128 v180, v[2:5] offset:18432
	v_mfma_f32_32x32x16_bf16 v[50:65], v[6:9], v[42:45], 0
	buffer_load_dwordx4 v[142:145], v183, s[40:43], 0 offen
	v_mfma_f32_32x32x16_bf16 v[2:17], v[38:41], v[10:13], 0
	s_waitcnt vmcnt(16)
	ds_write_b128 v180, v[34:37] offset:55296
	v_mfma_f32_32x32x16_bf16 v[34:49], v[38:41], v[42:45], 0
	s_movk_i32 s34, 0x5180
	ds_read_b128 v[186:189], v152 offset:64
	ds_read_b128 v[190:193], v152 offset:4672
	ds_read_b128 v[194:197], v182 offset:36928
	ds_read_b128 v[198:201], v182 offset:41536
	s_waitcnt vmcnt(15)
	ds_write_b128 v180, v[118:121] offset:23040
	buffer_load_dwordx4 v[118:121], v185, s[24:27], s34 offen
	s_waitcnt lgkmcnt(8)
	v_mfma_f32_32x32x16_bf16 v[18:33], v[138:141], v[134:137], v[18:33]
	s_waitcnt lgkmcnt(7)
	v_mfma_f32_32x32x16_bf16 v[50:65], v[138:141], v[130:133], v[50:65]
	v_mfma_f32_32x32x16_bf16 v[2:17], v[126:129], v[134:137], v[2:17]
	buffer_load_dwordx4 v[134:137], v183, s[40:43], s33 offen
	s_waitcnt vmcnt(16)
	ds_write_b128 v180, v[114:117] offset:59904
	v_mfma_f32_32x32x16_bf16 v[34:49], v[126:129], v[130:133], v[34:49]
	s_mov_b32 s34, 0xa180
	ds_read_b128 v[114:117], v152 offset:96
	ds_read_b128 v[126:129], v152 offset:4704
	ds_read_b128 v[130:133], v182 offset:36960
	ds_read_b128 v[138:141], v182 offset:41568
	s_waitcnt vmcnt(15)
	ds_write_b128 v180, v[110:113] offset:27648
	buffer_load_dwordx4 v[110:113], v185, s[24:27], s34 offen
	s_waitcnt lgkmcnt(8)
	v_mfma_f32_32x32x16_bf16 v[18:33], v[186:189], v[194:197], v[18:33]
	s_waitcnt lgkmcnt(7)
	v_mfma_f32_32x32x16_bf16 v[50:65], v[186:189], v[198:201], v[50:65]
	buffer_load_dwordx4 v[186:189], v183, s[40:43], s29 offen
	v_mfma_f32_32x32x16_bf16 v[2:17], v[190:193], v[194:197], v[2:17]
	s_waitcnt vmcnt(16)
	ds_write_b128 v180, v[102:105] offset:64512
	v_mfma_f32_32x32x16_bf16 v[34:49], v[190:193], v[198:201], v[34:49]
	s_mov_b32 s34, 0xf180
	buffer_load_dwordx4 v[102:105], v185, s[24:27], s34 offen
	s_waitcnt vmcnt(16)
	ds_write_b128 v180, v[106:109] offset:32256
	s_waitcnt lgkmcnt(4)
	v_mfma_f32_32x32x16_bf16 v[18:33], v[114:117], v[130:133], v[18:33]
	s_waitcnt lgkmcnt(3)
	v_mfma_f32_32x32x16_bf16 v[50:65], v[114:117], v[138:141], v[50:65]
	buffer_load_dwordx4 v[106:109], v183, s[40:43], s3 offen
	v_mfma_f32_32x32x16_bf16 v[2:17], v[126:129], v[130:133], v[2:17]
	s_waitcnt vmcnt(16)
	ds_write_b128 v184, v[86:89] offset:13824
	v_mfma_f32_32x32x16_bf16 v[34:49], v[126:129], v[138:141], v[34:49]
	s_waitcnt lgkmcnt(0)
	s_barrier
	ds_read_b128 v[86:89], v152 offset:18432
	ds_read_b128 v[114:117], v182 offset:55296
	ds_read_b128 v[126:129], v152 offset:18464
	ds_read_b128 v[130:133], v182 offset:55328
	ds_read_b128 v[138:141], v182 offset:59904
	ds_read_b128 v[190:193], v152 offset:23040
	ds_read_b128 v[194:197], v152 offset:23072
	ds_read_b128 v[198:201], v182 offset:59936
	s_waitcnt lgkmcnt(6)
	v_mfma_f32_32x32x16_bf16 v[18:33], v[86:89], v[114:117], v[18:33]
	s_waitcnt vmcnt(15)
	ds_write_b128 v180, v[98:101]
	s_waitcnt lgkmcnt(4)
	v_mfma_f32_32x32x16_bf16 v[50:65], v[86:89], v[138:141], v[50:65]
	s_waitcnt lgkmcnt(3)
	v_mfma_f32_32x32x16_bf16 v[2:17], v[190:193], v[114:117], v[2:17]
	s_waitcnt vmcnt(14)
	ds_write_b128 v180, v[90:93] offset:36864
	v_mfma_f32_32x32x16_bf16 v[34:49], v[190:193], v[138:141], v[34:49]
	ds_read_b128 v[86:89], v152 offset:18496
	ds_read_b128 v[90:93], v152 offset:23104
	ds_read_b128 v[98:101], v182 offset:55360
	ds_read_b128 v[114:117], v182 offset:59968
	v_mfma_f32_32x32x16_bf16 v[18:33], v[126:129], v[130:133], v[18:33]
	s_waitcnt vmcnt(13)
	ds_write_b128 v180, v[94:97] offset:4608
	s_waitcnt lgkmcnt(7)
	v_mfma_f32_32x32x16_bf16 v[50:65], v[126:129], v[198:201], v[50:65]
	v_mfma_f32_32x32x16_bf16 v[2:17], v[194:197], v[130:133], v[2:17]
	s_waitcnt vmcnt(12)
	ds_write_b128 v180, v[82:85] offset:41472
	v_mfma_f32_32x32x16_bf16 v[34:49], v[194:197], v[198:201], v[34:49]
	ds_read_b128 v[82:85], v152 offset:18528
	ds_read_b128 v[94:97], v152 offset:23136
	ds_read_b128 v[126:129], v182 offset:55392
	ds_read_b128 v[130:133], v182 offset:60000
	s_waitcnt lgkmcnt(7)
	v_mfma_f32_32x32x16_bf16 v[18:33], v[86:89], v[98:101], v[18:33]
	s_waitcnt vmcnt(11)
	ds_write_b128 v180, v[78:81] offset:9216
	s_waitcnt lgkmcnt(7)
	v_mfma_f32_32x32x16_bf16 v[50:65], v[86:89], v[114:117], v[50:65]
	v_mfma_f32_32x32x16_bf16 v[2:17], v[90:93], v[98:101], v[2:17]
	s_waitcnt vmcnt(10)
	ds_write_b128 v180, v[74:77] offset:46080
	v_mfma_f32_32x32x16_bf16 v[34:49], v[90:93], v[114:117], v[34:49]
	s_waitcnt lgkmcnt(3)
	v_mfma_f32_32x32x16_bf16 v[18:33], v[82:85], v[126:129], v[18:33]
	s_waitcnt vmcnt(9)
	ds_write_b128 v180, v[70:73] offset:13824
	s_waitcnt lgkmcnt(3)
	v_mfma_f32_32x32x16_bf16 v[50:65], v[82:85], v[130:133], v[50:65]
	v_mfma_f32_32x32x16_bf16 v[2:17], v[94:97], v[126:129], v[2:17]
	s_waitcnt vmcnt(8)
	ds_write_b128 v180, v[66:69] offset:50688
	v_mfma_f32_32x32x16_bf16 v[34:49], v[94:97], v[130:133], v[34:49]
	s_waitcnt lgkmcnt(0)
	s_barrier
	ds_read_b128 v[66:69], v152
	ds_read_b128 v[70:73], v182 offset:36864
	ds_read_b128 v[74:77], v152 offset:32
	ds_read_b128 v[78:81], v182 offset:36896
	ds_read_b128 v[82:85], v182 offset:41472
	ds_read_b128 v[86:89], v152 offset:4608
	ds_read_b128 v[90:93], v152 offset:4640
	ds_read_b128 v[94:97], v182 offset:41504
	s_waitcnt lgkmcnt(6)
	v_mfma_f32_32x32x16_bf16 v[18:33], v[66:69], v[70:73], v[18:33]
	s_waitcnt vmcnt(7)
	ds_write_b128 v180, v[122:125] offset:18432
	s_waitcnt lgkmcnt(4)
	v_mfma_f32_32x32x16_bf16 v[50:65], v[66:69], v[82:85], v[50:65]
	s_waitcnt lgkmcnt(3)
	v_mfma_f32_32x32x16_bf16 v[2:17], v[86:89], v[70:73], v[2:17]
	s_waitcnt vmcnt(6)
	ds_write_b128 v180, v[142:145] offset:55296
	v_mfma_f32_32x32x16_bf16 v[34:49], v[86:89], v[82:85], v[34:49]
	ds_read_b128 v[66:69], v152 offset:64
	ds_read_b128 v[70:73], v152 offset:4672
	ds_read_b128 v[82:85], v182 offset:36928
	ds_read_b128 v[86:89], v182 offset:41536
	v_mfma_f32_32x32x16_bf16 v[18:33], v[74:77], v[78:81], v[18:33]
	s_waitcnt vmcnt(5)
	ds_write_b128 v180, v[118:121] offset:23040
	s_waitcnt lgkmcnt(7)
	v_mfma_f32_32x32x16_bf16 v[50:65], v[74:77], v[94:97], v[50:65]
	v_mfma_f32_32x32x16_bf16 v[2:17], v[90:93], v[78:81], v[2:17]
	s_waitcnt vmcnt(4)
	ds_write_b128 v180, v[134:137] offset:59904
	v_mfma_f32_32x32x16_bf16 v[34:49], v[90:93], v[94:97], v[34:49]
	ds_read_b128 v[74:77], v152 offset:96
	ds_read_b128 v[78:81], v152 offset:4704
	ds_read_b128 v[90:93], v182 offset:36960
	ds_read_b128 v[94:97], v182 offset:41568
	s_waitcnt lgkmcnt(7)
	v_mfma_f32_32x32x16_bf16 v[18:33], v[66:69], v[82:85], v[18:33]
	s_waitcnt vmcnt(3)
	ds_write_b128 v180, v[110:113] offset:27648
	s_waitcnt lgkmcnt(7)
	v_mfma_f32_32x32x16_bf16 v[50:65], v[66:69], v[86:89], v[50:65]
	v_mfma_f32_32x32x16_bf16 v[2:17], v[70:73], v[82:85], v[2:17]
	s_waitcnt vmcnt(2)
	ds_write_b128 v180, v[186:189] offset:64512
	v_mfma_f32_32x32x16_bf16 v[34:49], v[70:73], v[86:89], v[34:49]
	s_waitcnt lgkmcnt(3)
	v_mfma_f32_32x32x16_bf16 v[18:33], v[74:77], v[90:93], v[18:33]
	s_waitcnt vmcnt(1)
	ds_write_b128 v180, v[102:105] offset:32256
	s_waitcnt lgkmcnt(3)
	v_mfma_f32_32x32x16_bf16 v[50:65], v[74:77], v[94:97], v[50:65]
	v_mfma_f32_32x32x16_bf16 v[2:17], v[78:81], v[90:93], v[2:17]
	s_waitcnt vmcnt(0)
	ds_write_b128 v184, v[106:109] offset:13824
	v_mfma_f32_32x32x16_bf16 v[34:49], v[78:81], v[94:97], v[34:49]
	s_waitcnt lgkmcnt(0)
	s_barrier
	ds_read_b128 v[66:69], v152 offset:18432
	ds_read_b128 v[70:73], v182 offset:55296
	ds_read_b128 v[74:77], v152 offset:18464
	ds_read_b128 v[78:81], v182 offset:55328
	ds_read_b128 v[82:85], v182 offset:59904
	ds_read_b128 v[86:89], v152 offset:23040
	ds_read_b128 v[90:93], v152 offset:23072
	ds_read_b128 v[94:97], v182 offset:59936
	s_waitcnt lgkmcnt(6)
	v_mfma_f32_32x32x16_bf16 v[18:33], v[66:69], v[70:73], v[18:33]
	s_waitcnt lgkmcnt(3)
	v_mfma_f32_32x32x16_bf16 v[50:65], v[66:69], v[82:85], v[50:65]
	s_waitcnt lgkmcnt(2)
	v_mfma_f32_32x32x16_bf16 v[2:17], v[86:89], v[70:73], v[2:17]
	v_mfma_f32_32x32x16_bf16 v[34:49], v[86:89], v[82:85], v[34:49]
	ds_read_b128 v[66:69], v152 offset:18496
	ds_read_b128 v[70:73], v152 offset:23104
	ds_read_b128 v[82:85], v182 offset:55360
	ds_read_b128 v[86:89], v182 offset:59968
	v_mfma_f32_32x32x16_bf16 v[18:33], v[74:77], v[78:81], v[18:33]
	s_waitcnt lgkmcnt(4)
	v_mfma_f32_32x32x16_bf16 v[50:65], v[74:77], v[94:97], v[50:65]
	v_mfma_f32_32x32x16_bf16 v[2:17], v[90:93], v[78:81], v[2:17]
	v_mfma_f32_32x32x16_bf16 v[34:49], v[90:93], v[94:97], v[34:49]
	ds_read_b128 v[74:77], v152 offset:18528
	ds_read_b128 v[78:81], v152 offset:23136
	ds_read_b128 v[90:93], v182 offset:55392
	ds_read_b128 v[94:97], v182 offset:60000
	s_waitcnt lgkmcnt(5)
	v_mfma_f32_32x32x16_bf16 v[18:33], v[66:69], v[82:85], v[18:33]
	s_waitcnt lgkmcnt(4)
	v_mfma_f32_32x32x16_bf16 v[50:65], v[66:69], v[86:89], v[50:65]
	v_mfma_f32_32x32x16_bf16 v[2:17], v[70:73], v[82:85], v[2:17]
	v_mfma_f32_32x32x16_bf16 v[34:49], v[70:73], v[86:89], v[34:49]
	s_waitcnt lgkmcnt(1)
	v_mfma_f32_32x32x16_bf16 v[18:33], v[74:77], v[90:93], v[18:33]
	s_waitcnt lgkmcnt(0)
	v_mfma_f32_32x32x16_bf16 v[50:65], v[74:77], v[94:97], v[50:65]
	v_mfma_f32_32x32x16_bf16 v[2:17], v[78:81], v[90:93], v[2:17]
	v_mfma_f32_32x32x16_bf16 v[34:49], v[78:81], v[94:97], v[34:49]
	v_lshl_or_b32 v66, v151, 2, v181
	s_movk_i32 s24, 0x210
	v_mul_lo_u32 v66, v66, s24
	v_lshl_add_u32 v66, v153, 2, v66
	s_barrier
	s_nop 4
	ds_write2_b32 v66, v18, v50 offset1:32
	ds_write2_b32 v66, v19, v51 offset0:132 offset1:164
	v_add_u32_e32 v18, 0x400, v66
	ds_write2_b32 v18, v20, v52 offset0:8 offset1:40
	ds_write2_b32 v18, v21, v53 offset0:140 offset1:172
	v_add_u32_e32 v18, 0x1000, v66
	ds_write2_b32 v18, v22, v54 offset0:32 offset1:64
	ds_write2_b32 v18, v23, v55 offset0:164 offset1:196
	v_add_u32_e32 v18, 0x1400, v66
	ds_write2_b32 v18, v24, v56 offset0:40 offset1:72
	ds_write2_b32 v18, v25, v57 offset0:172 offset1:204
	v_add_u32_e32 v18, 0x2000, v66
	ds_write2_b32 v18, v26, v58 offset0:64 offset1:96
	ds_write2_b32 v18, v27, v59 offset0:196 offset1:228
	v_add_u32_e32 v18, 0x2400, v66
	ds_write2_b32 v18, v28, v60 offset0:72 offset1:104
	ds_write2_b32 v18, v29, v61 offset0:204 offset1:236
	v_add_u32_e32 v18, 0x3000, v66
	ds_write2_b32 v18, v30, v62 offset0:96 offset1:128
	v_add_u32_e32 v18, 0x3200, v66
	ds_write2_b32 v18, v31, v63 offset0:100 offset1:132
	v_add_u32_e32 v18, 0x3400, v66
	ds_write2_b32 v18, v32, v64 offset0:104 offset1:136
	v_add_u32_e32 v18, 0x3600, v66
	ds_write2_b32 v18, v33, v65 offset0:108 offset1:140
	v_add_u32_e32 v18, 0x4000, v66
	ds_write2_b32 v18, v2, v34 offset0:128 offset1:160
	v_add_u32_e32 v2, 0x4400, v66
	ds_write2_b32 v2, v3, v35 offset0:4 offset1:36
	ds_write2_b32 v2, v4, v36 offset0:136 offset1:168
	v_add_u32_e32 v2, 0x4800, v66
	ds_write2_b32 v2, v5, v37 offset0:12 offset1:44
	v_add_u32_e32 v2, 0x5000, v66
	ds_write2_b32 v2, v6, v38 offset0:160 offset1:192
	v_add_u32_e32 v2, 0x5400, v66
	ds_write2_b32 v2, v7, v39 offset0:36 offset1:68
	ds_write2_b32 v2, v8, v40 offset0:168 offset1:200
	v_add_u32_e32 v2, 0x5800, v66
	ds_write2_b32 v2, v9, v41 offset0:44 offset1:76
	v_add_u32_e32 v2, 0x6000, v66
	ds_write2_b32 v2, v10, v42 offset0:192 offset1:224
	v_add_u32_e32 v2, 0x6400, v66
	ds_write2_b32 v2, v11, v43 offset0:68 offset1:100
	ds_write2_b32 v2, v12, v44 offset0:200 offset1:232
	v_add_u32_e32 v2, 0x6800, v66
	s_mul_hi_u32 s25, s23, 0x440000
	s_mul_i32 s23, s23, 0x440000
	ds_write2_b32 v2, v13, v45 offset0:76 offset1:108
	v_add_u32_e32 v2, 0x7200, v66
	s_add_u32 s24, s60, s23
	ds_write2_b32 v2, v14, v46 offset0:96 offset1:128
	v_add_u32_e32 v2, 0x7400, v66
	s_addc_u32 s25, s61, s25
	s_lshl_b32 s1, s1, 9
	s_lshl_b32 s0, s0, 7
	ds_write2_b32 v2, v15, v47 offset0:100 offset1:132
	v_add_u32_e32 v2, 0x7600, v66
	s_or_b32 s0, s1, s0
	ds_write2_b32 v2, v16, v48 offset0:104 offset1:136
	v_add_u32_e32 v2, 0x7800, v66
	v_add_u32_e32 v68, s0, v177
	v_mov_b64_e32 v[66:67], s[24:25]
	v_mad_i64_i32 v[66:67], s[0:1], v68, s93, v[66:67]
	s_lshl_b32 s96, s22, 1
	ds_write2_b32 v2, v17, v49 offset0:108 offset1:140
	s_waitcnt lgkmcnt(0)
	s_barrier
	ds_read_b128 v[2:5], v178
	ds_read_b128 v[6:9], v178 offset:16
	ds_read_b128 v[10:13], v178 offset:32
	ds_read_b128 v[14:17], v178 offset:48
	ds_read_b128 v[18:21], v178 offset:64
	ds_read_b128 v[22:25], v178 offset:80
	ds_read_b128 v[26:29], v178 offset:96
	ds_read_b128 v[30:33], v178 offset:112
	ds_read_b128 v[34:37], v178 offset:128
	ds_read_b128 v[38:41], v178 offset:144
	ds_read_b128 v[42:45], v178 offset:160
	ds_read_b128 v[46:49], v178 offset:176
	ds_read_b128 v[50:53], v178 offset:192
	ds_read_b128 v[54:57], v178 offset:208
	ds_read_b128 v[58:61], v178 offset:224
	ds_read_b128 v[62:65], v178 offset:240
	v_lshl_add_u64 v[66:67], v[66:67], 0, s[96:97]
	v_lshl_add_u64 v[66:67], v[66:67], 0, v[146:147]
	s_waitcnt lgkmcnt(14)
	v_cvt_pk_bf16_f32 v9, v8, v9
	v_cvt_pk_bf16_f32 v8, v6, v7
	v_cvt_pk_bf16_f32 v7, v4, v5
	v_cvt_pk_bf16_f32 v6, v2, v3
	s_waitcnt lgkmcnt(12)
	v_cvt_pk_bf16_f32 v5, v16, v17
	v_cvt_pk_bf16_f32 v4, v14, v15
	v_cvt_pk_bf16_f32 v3, v12, v13
	v_cvt_pk_bf16_f32 v2, v10, v11
	global_store_dwordx4 v[66:67], v[2:5], off offset:16
	s_mov_b32 s96, 0x800000
	s_waitcnt lgkmcnt(10)
	v_cvt_pk_bf16_f32 v5, v24, v25
	v_cvt_pk_bf16_f32 v4, v22, v23
	v_cvt_pk_bf16_f32 v3, v20, v21
	v_cvt_pk_bf16_f32 v2, v18, v19
	global_store_dwordx4 v[66:67], v[2:5], off offset:32
	global_store_dwordx4 v[66:67], v[6:9], off
	s_waitcnt lgkmcnt(8)
	v_cvt_pk_bf16_f32 v5, v32, v33
	v_cvt_pk_bf16_f32 v4, v30, v31
	v_cvt_pk_bf16_f32 v3, v28, v29
	v_cvt_pk_bf16_f32 v2, v26, v27
	global_store_dwordx4 v[66:67], v[2:5], off offset:48
	s_waitcnt lgkmcnt(6)
	s_nop 0
	v_cvt_pk_bf16_f32 v5, v40, v41
	v_cvt_pk_bf16_f32 v4, v38, v39
	v_cvt_pk_bf16_f32 v3, v36, v37
	v_cvt_pk_bf16_f32 v2, v34, v35
	global_store_dwordx4 v[66:67], v[2:5], off offset:64
	s_waitcnt lgkmcnt(4)
	s_nop 0
	v_cvt_pk_bf16_f32 v5, v48, v49
	v_cvt_pk_bf16_f32 v4, v46, v47
	v_cvt_pk_bf16_f32 v3, v44, v45
	v_cvt_pk_bf16_f32 v2, v42, v43
	global_store_dwordx4 v[66:67], v[2:5], off offset:80
	s_waitcnt lgkmcnt(2)
	s_nop 0
	v_cvt_pk_bf16_f32 v5, v56, v57
	v_cvt_pk_bf16_f32 v4, v54, v55
	v_cvt_pk_bf16_f32 v3, v52, v53
	v_cvt_pk_bf16_f32 v2, v50, v51
	global_store_dwordx4 v[66:67], v[2:5], off offset:96
	s_waitcnt lgkmcnt(0)
	s_nop 0
	v_cvt_pk_bf16_f32 v5, v64, v65
	v_cvt_pk_bf16_f32 v4, v62, v63
	v_cvt_pk_bf16_f32 v3, v60, v61
	v_cvt_pk_bf16_f32 v2, v58, v59
	global_store_dwordx4 v[66:67], v[2:5], off offset:112
	s_cbranch_execnz .LBB0_25

.LBB0_46:
	v_readlane_b32 s34, v246, 40
	v_readlane_b32 s35, v246, 41
	s_waitcnt lgkmcnt(0)
	s_barrier
	s_add_i32 s35, s34, s35
	v_writelane_b32 v246, s35, 40
	s_and_b32 s35, s34, 7
	s_lshl_b32 s35, s35, 16
	s_lshr_b32 s20, s34, 3
	s_or_b32 s20, s20, s35
	s_cmp_lt_u32 s34, 640
	s_cselect_b32 s20, s20, -1
	s_cmp_lt_i32 s20, 0
	s_cbranch_scc1 .LBB0_45
	s_lshr_b32 s40, s20, 16
	s_and_b32 s21, s20, 0xffff
	s_cmp_gt_u32 s21, 15
	s_cbranch_scc0 .LBB0_58
	s_lshl_b32 s24, s21, 4
	s_lshl_b32 s0, s40, 10
	s_and_b32 s24, s24, 0xfff00
	s_add_i32 s0, s0, s24
	s_bfe_u32 s2, s20, 0x10003
	s_and_b32 s1, s20, 7
	s_addk_i32 s0, 0xff00
	s_mov_b64 s[24:25], s[66:67]
	s_cbranch_execz .LBB0_59
	s_movk_i32 s20, 0x100
	s_movk_i32 s51, 0x240
	s_branch .LBB0_60

.LBB0_72:
	v_readlane_b32 s34, v246, 40
	v_readlane_b32 s35, v246, 41
	s_waitcnt lgkmcnt(0)
	s_barrier
	s_add_i32 s35, s34, s35
	v_writelane_b32 v246, s35, 40
	s_and_b32 s35, s34, 7
	s_lshl_b32 s35, s35, 16
	s_lshr_b32 s48, s34, 3
	s_or_b32 s48, s48, s35
	s_cmp_lt_u32 s34, 512
	s_cselect_b32 s48, s48, -1
	s_mov_b64 s[0:1], -1
	s_cmp_lt_i32 s48, 0
	s_cbranch_scc1 .LBB0_71
	s_lshr_b32 s54, s48, 16
	s_and_b32 s55, s48, 0xffff
	s_cmp_lt_u32 s55, 32
	v_lshlrev_b32_e32 v146, 1, v98
	s_cbranch_scc0 .LBB0_107
	s_lshr_b32 s0, s48, 15
	s_and_b32 s2, s0, 4
	s_lshl_b32 s0, s54, 1
	s_and_b32 s0, s0, 2
	s_bfe_u32 s1, s48, 0x10003
	s_lshr_b32 s20, s48, 18
	s_or_b32 s0, s1, s0
	s_or_b32 s25, s0, s2
	s_lshl_b32 s21, s20, 10
	s_lshl_b32 s0, s48, 7
	s_addk_i32 s21, 0x2000
	s_and_b32 s24, s0, 0x380
	s_cmp_gt_u32 s55, 15
	s_cselect_b64 s[0:1], -1, 0
	s_and_b64 s[36:37], s[0:1], exec
	s_cselect_b32 s34, 0x500, 0
	s_lshl_b32 s51, s25, 6
	s_add_i32 s34, s51, s34
	v_add_u32_e32 v2, s24, v101
	s_lshl_b32 s96, s34, 1
	v_add_u32_e32 v151, s21, v2
	v_mov_b64_e32 v[4:5], s[10:11]
	s_movk_i32 s34, 0x1400
	v_mad_i64_i32 v[144:145], s[36:37], v151, s34, v[4:5]
	v_lshl_add_u64 v[4:5], v[144:145], 0, s[96:97]
	v_lshl_add_u64 v[4:5], v[4:5], 0, v[146:147]
	global_load_dwordx4 v[78:81], v[4:5], off
	global_load_dwordx4 v[74:77], v[4:5], off offset:32
	global_load_dwordx4 v[70:73], v[4:5], off offset:64
	global_load_dwordx4 v[66:69], v[4:5], off offset:96
	s_cmp_lt_u32 s55, 16
	s_cbranch_scc1 .LBB0_84
	s_or_b32 s36, s25, s58
	s_ashr_i32 s37, s36, 31
	v_readlane_b32 s60, v248, 50
	s_lshl_b64 s[36:37], s[36:37], 2
	v_readlane_b32 s74, v247, 0
	v_readlane_b32 s75, v247, 1
	s_add_u32 s36, s74, s36
	s_addc_u32 s37, s75, s37
	global_load_dword v3, v147, s[36:37]
	v_readlane_b32 s61, v248, 51
	v_readlane_b32 s62, v248, 52
	v_readlane_b32 s63, v248, 53
	v_readlane_b32 s64, v248, 54
	v_readlane_b32 s65, v248, 55
	v_readlane_b32 s66, v248, 56
	v_readlane_b32 s67, v248, 57
	v_readlane_b32 s68, v248, 58
	v_readlane_b32 s69, v248, 59
	v_readlane_b32 s70, v248, 60
	v_readlane_b32 s71, v248, 61
	v_readlane_b32 s72, v248, 62
	v_readlane_b32 s73, v248, 63
	v_readlane_b32 s60, v248, 21
	v_readlane_b32 s61, v248, 22
	v_readlane_b32 s62, v248, 23
	v_readlane_b32 s63, v248, 24
	v_readlane_b32 s64, v248, 25
	v_readlane_b32 s65, v248, 26
	v_readlane_b32 s66, v248, 27
	v_readlane_b32 s67, v248, 28
	v_readlane_b32 s68, v248, 29
	v_readlane_b32 s69, v248, 30
	v_readlane_b32 s70, v248, 31
	v_readlane_b32 s71, v248, 32
	v_readlane_b32 s72, v248, 33
	v_readlane_b32 s73, v248, 34
	v_readlane_b32 s74, v248, 35
	v_readlane_b32 s75, v248, 36
	v_mov_b32_e32 v200, v103
	s_waitcnt vmcnt(0)
	v_mul_f32_e32 v201, 0x3fb8aa3b, v3
	s_branch .LBB0_85

.LBB0_122:
.LBB0_123:
	v_readlane_b32 s34, v246, 40
	v_readlane_b32 s35, v246, 41
	s_waitcnt lgkmcnt(0)
	s_barrier
	s_add_i32 s35, s34, s35
	v_writelane_b32 v246, s35, 40
	s_and_b32 s35, s34, 7
	s_lshl_b32 s35, s35, 16
	s_lshr_b32 s0, s34, 3
	s_or_b32 s0, s0, s35
	s_cmp_lt_u32 s34, 640
	s_cselect_b32 s0, s0, -1
	s_cmp_lt_i32 s0, 0
	s_cbranch_scc1 .LBB0_145
	s_lshr_b32 s1, s0, 16
	s_and_b32 s2, s0, 0xfff8
	s_add_i32 s1, s1, s2
	s_and_b32 s51, s0, 7
	s_lshl_b32 s2, s1, 7
	s_mul_i32 s1, s1, 0x44000
	s_mul_hi_u32 s0, s2, 0x880
	s_add_u32 s40, s12, s1
	s_addc_u32 s0, s13, s0
	s_mul_i32 s1, s51, 0x44000
	v_mov_b32_e32 v136, v0
	s_add_u32 s44, s49, s1
	s_movk_i32 s1, 0x440
	v_ashrrev_i32_e32 v34, 3, v136
	v_lshlrev_b32_e32 v3, 3, v136
	v_mul_lo_u32 v2, v34, s1
	v_and_b32_e32 v35, 56, v3
	s_addc_u32 vcc_lo, s96, 0
	v_or_b32_e32 v2, v2, v35
	s_and_b32 s41, s0, 0xffff
	v_lshlrev_b32_e32 v140, 1, v2
	s_mov_b32 s24, s40
	s_mov_b32 s25, s41
	s_and_b32 s45, vcc_lo, 0xffff
	s_mov_b32 s46, s26
	s_mov_b32 s47, s27
	v_readlane_b32 s0, v246, 22
	v_readlane_b32 s70, v248, 7
	v_readlane_b32 s71, v248, 8
	s_sub_u32 s1, s2, 0x2000
	s_lshr_b32 s1, s1, 10
	s_add_i32 s1, s1, 1
	s_cmp_lt_u32 s2, 0x2000
	s_cselect_b32 s1, 0, s1
	s_add_i32 s0, s0, s1
	s_mul_i32 s0, s0, 0x3000
	s_lshl_b32 s1, s51, 9
	s_add_i32 s0, s0, s1
	s_add_u32 s60, s4, s0
	s_addc_u32 s61, s5, 0
	s_add_u32 s62, s60, 0x2000
	s_addc_u32 s63, s61, 0
	s_add_u32 s64, s60, 0xa000
	s_addc_u32 s65, s61, 0
	s_add_u32 s66, s98, s1
	s_addc_u32 s67, s99, 0
	s_lshl_b32 s0, s2, 12
	s_add_u32 s70, s70, s0
	s_addc_u32 s71, s71, 0
	s_cmp_lg_u64 s[22:23], 0
	s_cbranch_scc1 .Lg2_xs_out
	s_cmp_lt_u32 s2, 0x2000
	s_cbranch_scc1 .Lg2_xs_ctx
	s_sub_u32 s1, s2, 0x2000
	s_lshl_b32 s1, s1, 12
	s_add_u32 s68, s78, s1
	s_addc_u32 s69, s79, 0
	s_branch .Lg2_xs_done

.LBB0_150:
.LBB0_151:
	v_readlane_b32 s34, v246, 40
	v_readlane_b32 s35, v246, 41
	s_waitcnt lgkmcnt(0)
	s_barrier
	s_add_i32 s35, s34, s35
	v_writelane_b32 v246, s35, 40
	s_and_b32 s35, s34, 7
	s_lshl_b32 s35, s35, 16
	s_lshr_b32 s54, s34, 3
	s_or_b32 s54, s54, s35
	s_cmp_lt_u32 s34, 1280
	s_cselect_b32 s54, s54, -1
	s_cmp_lt_i32 s54, 0
	s_cbranch_scc1 .LBB0_176
	s_lshr_b32 s1, s54, 1
	s_lshr_b32 s0, s54, 17
	s_and_b32 s20, s1, 0x7ffc
	s_add_i32 s20, s20, s0
	s_lshr_b32 s0, s54, 13
	s_and_b32 s96, s0, 8
	s_and_b32 s41, s54, 7
	s_or_b32 s2, s96, s41
	s_mov_b32 s24, 0x800000
	s_lshl_b32 s55, s20, 7
	s_lshl_b32 s51, s2, 7
	s_and_saveexec_b64 s[0:1], s[38:39]
	s_xor_b64 s[0:1], exec, s[0:1]
	s_cbranch_execz .LBB0_162
	s_add_i32 s21, s55, 0xffffe000
	s_lshr_b32 s21, s21, 10
	s_add_i32 s21, s21, 1
	s_cmp_gt_u32 s20, 63
	s_cselect_b32 s20, s21, 0
	s_add_i32 s20, s53, s20
	v_readlane_b32 s56, v248, 1
	s_mul_hi_i32 s21, s20, 0x3000
	s_mulk_i32 s20, 0x3000
	v_readlane_b32 s70, v248, 15
	v_readlane_b32 s71, v248, 16
	s_add_u32 s20, s70, s20
	s_addc_u32 s21, s71, s21
	s_lshl_b32 s22, s51, 2
	s_add_u32 s20, s20, s22
	s_addc_u32 s21, s21, 0
	v_lshl_add_u64 v[2:3], v[130:131], 2, s[20:21]
	global_load_dword v135, v[2:3], off offset:-512
	v_readlane_b32 s60, v248, 5
	v_readlane_b32 s61, v248, 6
	v_readlane_b32 s62, v248, 7
	v_readlane_b32 s63, v248, 8
	v_readlane_b32 s64, v248, 9
	v_readlane_b32 s65, v248, 10
	v_readlane_b32 s66, v248, 11
	v_readlane_b32 s67, v248, 12
	v_readlane_b32 s68, v248, 13
	v_readlane_b32 s69, v248, 14
	v_readlane_b32 s60, v248, 21
	v_readlane_b32 s57, v248, 2
	v_readlane_b32 s58, v248, 3
	v_readlane_b32 s59, v248, 4
	v_readlane_b32 s61, v248, 22
	v_readlane_b32 s62, v248, 23
	v_readlane_b32 s63, v248, 24
	v_readlane_b32 s64, v248, 25
	v_readlane_b32 s65, v248, 26
	v_readlane_b32 s66, v248, 27
	v_readlane_b32 s67, v248, 28
	v_readlane_b32 s68, v248, 29
	v_readlane_b32 s69, v248, 30
	v_readlane_b32 s70, v248, 31
	v_readlane_b32 s71, v248, 32
	v_readlane_b32 s72, v248, 33
	v_readlane_b32 s73, v248, 34
	v_readlane_b32 s74, v248, 35
	v_readlane_b32 s75, v248, 36

.LBB0_194:
.LBB0_195:
	v_readlane_b32 s34, v246, 40
	v_readlane_b32 s35, v246, 41
	s_waitcnt lgkmcnt(0)
	s_barrier
	s_add_i32 s35, s34, s35
	v_writelane_b32 v246, s35, 40
	s_and_b32 s35, s34, 7
	s_lshl_b32 s35, s35, 16
	s_lshr_b32 s0, s34, 3
	s_or_b32 s0, s0, s35
	s_cmp_lt_u32 s34, 1600
	s_cselect_b32 s0, s0, -1
	s_cmp_lt_i32 s0, 0
	s_cbranch_scc1 .LBB0_214
	s_and_b32 s1, s0, 0xffff
	s_mul_i32 s1, s1, 0xcccd
	s_lshr_b32 s1, s1, 19
	s_bfe_i32 s2, s0, 0x10010
	s_and_b32 s51, s2, 10
	s_mul_i32 s2, s1, 10
	s_sub_i32 s2, s0, s2
	s_and_b32 s2, s2, 0xffff
	s_lshr_b32 s0, s0, 10
	s_add_i32 s51, s51, s2
	s_lshl_b32 s39, s1, 9
	s_and_b32 s0, s0, 0x1fff80
	v_cndmask_b32_e64 v3, 0, 1, s[48:49]
	s_mov_b32 s34, 0x800000
	s_add_i32 s39, s39, s0
	s_lshl_b32 s96, s51, 7
	v_mov_b32_e32 v2, 0
	v_cmp_ne_u32_e64 s[40:41], 1, v3
	s_andn2_b64 vcc, exec, s[48:49]
	v_mov_b32_e32 v146, 0
	s_cbranch_vccnz .LBB0_210
	s_mov_b64 s[0:1], exec
	v_readlane_b32 s20, v246, 26
	v_readlane_b32 s21, v246, 27
	s_and_b64 s[20:21], s[0:1], s[20:21]
	s_xor_b64 s[0:1], s[20:21], s[0:1]
	s_mov_b64 exec, s[20:21]
	s_cbranch_execz .LBB0_207
	v_sub_co_u32_e32 v3, vcc, s39, v171
	s_nop 0
	v_readfirstlane_b32 s2, v3
	s_lshr_b32 s2, s2, 10
	s_add_i32 s2, s2, 1
	s_and_b64 s[20:21], vcc, exec
	s_cselect_b32 s2, 0, s2
	v_readlane_b32 s20, v246, 24
	s_add_i32 s2, s2, s20
	v_readlane_b32 s52, v248, 1
	s_mul_hi_u32 s20, s2, 0x3000
	s_mulk_i32 s2, 0x3000
	v_readlane_b32 s66, v248, 15
	v_readlane_b32 s67, v248, 16
	s_add_u32 s2, s66, s2
	s_addc_u32 s21, s67, s20
	s_lshl_b32 s20, s96, 2
	s_add_u32 s20, s2, s20
	s_addc_u32 s21, s21, 0
	v_lshl_add_u64 v[4:5], v[130:131], 2, s[20:21]
	global_load_dword v146, v[4:5], off offset:-512
	v_readlane_b32 s60, v248, 9
	v_readlane_b32 s61, v248, 10
	v_readlane_b32 s62, v248, 11
	v_readlane_b32 s63, v248, 12
	v_readlane_b32 s64, v248, 13
	v_readlane_b32 s65, v248, 14
	v_readlane_b32 s60, v248, 21
	v_readlane_b32 s53, v248, 2
	v_readlane_b32 s54, v248, 3
	v_readlane_b32 s55, v248, 4
	v_readlane_b32 s56, v248, 5
	v_readlane_b32 s57, v248, 6
	v_readlane_b32 s58, v248, 7
	v_readlane_b32 s59, v248, 8
	v_readlane_b32 s61, v248, 22
	v_readlane_b32 s62, v248, 23
	v_readlane_b32 s63, v248, 24
	v_readlane_b32 s64, v248, 25
	v_readlane_b32 s65, v248, 26
	v_readlane_b32 s66, v248, 27
	v_readlane_b32 s67, v248, 28
	v_readlane_b32 s68, v248, 29
	v_readlane_b32 s69, v248, 30
	v_readlane_b32 s70, v248, 31
	v_readlane_b32 s71, v248, 32
	v_readlane_b32 s72, v248, 33
	v_readlane_b32 s73, v248, 34
	v_readlane_b32 s74, v248, 35
	v_readlane_b32 s75, v248, 36
